# 32x32x16 attention loop: two alternating f32 row-sum accumulators (shorter dependent add chains)
# baseline (speedup 1.0000x reference)
.Lattn_nf_loop:
	s_and_b32 s10, s15, 1
	s_mul_i32 s6, s10, 0x8800
	v_add_u32_e32 v136, s6, v137
	v_add_u32_e32 v170, s6, v183
	s_sub_u32 s10, 0x8800, s6
	ds_read_b128 v[98:101], v136 offset:0
	ds_read_b128 v[102:105], v136 offset:32
	ds_read_b128 v[106:109], v136 offset:64
	ds_read_b128 v[110:113], v136 offset:96
	v_add_u32_e32 v171, s10, v126
	v_add_u32_e32 v173, s10, v127
	global_load_dwordx4 v[82:85], v124, s[64:65]
	global_load_dwordx4 v[86:89], v124, s[66:67]
	global_load_dwordx4 v[90:93], v124, s[68:69]
	global_load_dwordx4 v[94:97], v124, s[70:71]
	v_add_u32_e32 v124, s36, v124
	s_waitcnt lgkmcnt(3)
	v_mfma_f32_32x32x16_bf16 v[138:153], v[98:101], v[10:13], 0
	ds_read_b128 v[98:101], v136 offset:8704
	s_waitcnt lgkmcnt(3)
	v_mfma_f32_32x32x16_bf16 v[138:153], v[102:105], v[14:17], v[138:153]
	ds_read_b128 v[102:105], v136 offset:8736
	s_waitcnt lgkmcnt(3)
	v_mfma_f32_32x32x16_bf16 v[138:153], v[106:109], v[2:5], v[138:153]
	ds_read_b128 v[106:109], v136 offset:8768
	s_waitcnt lgkmcnt(3)
	v_mfma_f32_32x32x16_bf16 v[138:153], v[110:113], v[6:9], v[138:153]
	ds_read_b128 v[110:113], v136 offset:8800
	ds_read_b128 v[128:131], v170 offset:0
	ds_read_b128 v[184:187], v170 offset:8704
	ds_read_b128 v[188:191], v170 offset:17408
	ds_read_b128 v[192:195], v170 offset:26112
	s_waitcnt lgkmcnt(7)
	v_mfma_f32_32x32x16_bf16 v[154:169], v[98:101], v[10:13], 0
	ds_read_b128 v[98:101], v136 offset:17408
	s_nop 3
	v_exp_f32_e32 v138, v138
	v_exp_f32_e32 v139, v139
	v_exp_f32_e32 v140, v140
	v_exp_f32_e32 v141, v141
	v_exp_f32_e32 v142, v142
	v_exp_f32_e32 v143, v143
	s_waitcnt lgkmcnt(7)
	v_mfma_f32_32x32x16_bf16 v[154:169], v[102:105], v[14:17], v[154:169]
	ds_read_b128 v[102:105], v136 offset:17440
	v_exp_f32_e32 v144, v144
	v_exp_f32_e32 v145, v145
	v_add_f32_e32 v122, v138, v122
	v_add_f32_e32 v123, v139, v123
	v_add_f32_e32 v122, v140, v122
	v_add_f32_e32 v123, v141, v123
	v_add_f32_e32 v122, v142, v122
	v_add_f32_e32 v123, v143, v123
	v_add_f32_e32 v122, v144, v122
	v_add_f32_e32 v123, v145, v123
	v_cvt_pk_bf16_f32 v114, v138, v139
	v_cvt_pk_bf16_f32 v115, v140, v141
	v_cvt_pk_bf16_f32 v116, v142, v143
	v_cvt_pk_bf16_f32 v117, v144, v145
	ds_read_b128 v[196:199], v170 offset:32
	ds_read_b128 v[216:219], v170 offset:8736
	ds_read_b128 v[200:203], v170 offset:17440
	ds_read_b128 v[204:207], v170 offset:26144
	s_waitcnt lgkmcnt(11)
	v_mfma_f32_32x32x16_bf16 v[154:169], v[106:109], v[2:5], v[154:169]
	ds_read_b128 v[106:109], v136 offset:17472
	v_exp_f32_e32 v146, v146
	v_exp_f32_e32 v147, v147
	s_waitcnt lgkmcnt(11)
	v_mfma_f32_32x32x16_bf16 v[154:169], v[110:113], v[6:9], v[154:169]
	ds_read_b128 v[110:113], v136 offset:17504
	v_exp_f32_e32 v148, v148
	v_exp_f32_e32 v149, v149
	s_waitcnt lgkmcnt(11)
	v_mfma_f32_32x32x16_bf16 v[18:33], v[128:131], v[114:117], v[18:33]
	v_exp_f32_e32 v150, v150
	v_exp_f32_e32 v151, v151
	s_waitcnt lgkmcnt(10)
	v_mfma_f32_32x32x16_bf16 v[34:49], v[184:187], v[114:117], v[34:49]
	v_exp_f32_e32 v152, v152
	v_exp_f32_e32 v153, v153
	s_waitcnt lgkmcnt(9)
	v_mfma_f32_32x32x16_bf16 v[50:65], v[188:191], v[114:117], v[50:65]
	v_add_f32_e32 v122, v146, v122
	v_add_f32_e32 v123, v147, v123
	v_add_f32_e32 v122, v148, v122
	v_add_f32_e32 v123, v149, v123
	s_waitcnt lgkmcnt(8)
	v_mfma_f32_32x32x16_bf16 v[66:81], v[192:195], v[114:117], v[66:81]
	v_add_f32_e32 v122, v150, v122
	v_add_f32_e32 v123, v151, v123
	v_add_f32_e32 v122, v152, v122
	v_add_f32_e32 v123, v153, v123
	v_cvt_pk_bf16_f32 v118, v146, v147
	v_cvt_pk_bf16_f32 v119, v148, v149
	v_cvt_pk_bf16_f32 v120, v150, v151
	v_cvt_pk_bf16_f32 v121, v152, v153
	ds_read_b128 v[128:131], v170 offset:64
	ds_read_b128 v[184:187], v170 offset:8768
	ds_read_b128 v[188:191], v170 offset:17472
	ds_read_b128 v[192:195], v170 offset:26176
	s_waitcnt lgkmcnt(11)
	v_mfma_f32_32x32x16_bf16 v[138:153], v[98:101], v[10:13], 0
	ds_read_b128 v[98:101], v136 offset:26112
	v_exp_f32_e32 v154, v154
	v_exp_f32_e32 v155, v155
	s_waitcnt lgkmcnt(11)
	v_mfma_f32_32x32x16_bf16 v[138:153], v[102:105], v[14:17], v[138:153]
	ds_read_b128 v[102:105], v136 offset:26144
	v_exp_f32_e32 v156, v156
	v_exp_f32_e32 v157, v157
	s_waitcnt lgkmcnt(11)
	v_mfma_f32_32x32x16_bf16 v[18:33], v[196:199], v[118:121], v[18:33]
	v_exp_f32_e32 v158, v158
	v_exp_f32_e32 v159, v159
	s_waitcnt lgkmcnt(10)
	v_mfma_f32_32x32x16_bf16 v[34:49], v[216:219], v[118:121], v[34:49]
	v_exp_f32_e32 v160, v160
	v_exp_f32_e32 v161, v161
	s_waitcnt lgkmcnt(9)
	v_mfma_f32_32x32x16_bf16 v[50:65], v[200:203], v[118:121], v[50:65]
	v_add_f32_e32 v122, v154, v122
	v_add_f32_e32 v123, v155, v123
	v_add_f32_e32 v122, v156, v122
	v_add_f32_e32 v123, v157, v123
	s_waitcnt lgkmcnt(8)
	v_mfma_f32_32x32x16_bf16 v[66:81], v[204:207], v[118:121], v[66:81]
	v_add_f32_e32 v122, v158, v122
	v_add_f32_e32 v123, v159, v123
	v_add_f32_e32 v122, v160, v122
	v_add_f32_e32 v123, v161, v123
	v_cvt_pk_bf16_f32 v114, v154, v155
	v_cvt_pk_bf16_f32 v115, v156, v157
	v_cvt_pk_bf16_f32 v116, v158, v159
	v_cvt_pk_bf16_f32 v117, v160, v161
	ds_read_b128 v[196:199], v170 offset:96
	ds_read_b128 v[216:219], v170 offset:8800
	ds_read_b128 v[200:203], v170 offset:17504
	ds_read_b128 v[204:207], v170 offset:26208
	s_waitcnt lgkmcnt(11)
	v_mfma_f32_32x32x16_bf16 v[138:153], v[106:109], v[2:5], v[138:153]
	ds_read_b128 v[106:109], v136 offset:26176
	v_exp_f32_e32 v162, v162
	v_exp_f32_e32 v163, v163
	s_waitcnt lgkmcnt(11)
	v_mfma_f32_32x32x16_bf16 v[138:153], v[110:113], v[6:9], v[138:153]
	ds_read_b128 v[110:113], v136 offset:26208
	v_exp_f32_e32 v164, v164
	v_exp_f32_e32 v165, v165
	s_waitcnt lgkmcnt(11)
	v_mfma_f32_32x32x16_bf16 v[18:33], v[128:131], v[114:117], v[18:33]
	v_exp_f32_e32 v166, v166
	v_exp_f32_e32 v167, v167
	s_waitcnt lgkmcnt(10)
	v_mfma_f32_32x32x16_bf16 v[34:49], v[184:187], v[114:117], v[34:49]
	v_exp_f32_e32 v168, v168
	v_exp_f32_e32 v169, v169
	s_waitcnt lgkmcnt(9)
	v_mfma_f32_32x32x16_bf16 v[50:65], v[188:191], v[114:117], v[50:65]
	v_add_f32_e32 v122, v162, v122
	v_add_f32_e32 v123, v163, v123
	v_add_f32_e32 v122, v164, v122
	v_add_f32_e32 v123, v165, v123
	s_waitcnt lgkmcnt(8)
	v_mfma_f32_32x32x16_bf16 v[66:81], v[192:195], v[114:117], v[66:81]
	v_add_f32_e32 v122, v166, v122
	v_add_f32_e32 v123, v167, v123
	v_add_f32_e32 v122, v168, v122
	v_add_f32_e32 v123, v169, v123
	v_cvt_pk_bf16_f32 v118, v162, v163
	v_cvt_pk_bf16_f32 v119, v164, v165
	v_cvt_pk_bf16_f32 v120, v166, v167
	v_cvt_pk_bf16_f32 v121, v168, v169
	ds_read_b128 v[128:131], v170 offset:128
	ds_read_b128 v[184:187], v170 offset:8832
	ds_read_b128 v[188:191], v170 offset:17536
	ds_read_b128 v[192:195], v170 offset:26240
	s_waitcnt lgkmcnt(11)
	v_mfma_f32_32x32x16_bf16 v[154:169], v[98:101], v[10:13], 0
	v_exp_f32_e32 v138, v138
	s_waitcnt lgkmcnt(10)
	v_mfma_f32_32x32x16_bf16 v[154:169], v[102:105], v[14:17], v[154:169]
	v_exp_f32_e32 v139, v139
	v_exp_f32_e32 v140, v140
	s_waitcnt lgkmcnt(9)
	v_mfma_f32_32x32x16_bf16 v[18:33], v[196:199], v[118:121], v[18:33]
	v_exp_f32_e32 v141, v141
	v_exp_f32_e32 v142, v142
	s_waitcnt vmcnt(3)
	ds_write_b128 v171, v[82:85] offset:0
	s_waitcnt vmcnt(2)
	ds_write_b128 v171, v[86:89] offset:8704
	s_waitcnt vmcnt(1)
	ds_write_b128 v171, v[90:93] offset:17408
	s_waitcnt vmcnt(0)
	ds_write_b128 v171, v[94:97] offset:26112
	v_exp_f32_e32 v143, v143
	s_waitcnt lgkmcnt(12)
	v_mfma_f32_32x32x16_bf16 v[34:49], v[216:219], v[118:121], v[34:49]
	v_exp_f32_e32 v144, v144
	v_exp_f32_e32 v145, v145
	v_add_f32_e32 v122, v138, v122
	s_waitcnt lgkmcnt(11)
	v_mfma_f32_32x32x16_bf16 v[50:65], v[200:203], v[118:121], v[50:65]
	v_add_f32_e32 v123, v139, v123
	v_add_f32_e32 v122, v140, v122
	v_add_f32_e32 v123, v141, v123
	s_waitcnt lgkmcnt(10)
	v_mfma_f32_32x32x16_bf16 v[66:81], v[204:207], v[118:121], v[66:81]
	v_add_f32_e32 v122, v142, v122
	v_add_f32_e32 v123, v143, v123
	v_add_f32_e32 v122, v144, v122
	v_add_f32_e32 v123, v145, v123
	v_cvt_pk_bf16_f32 v114, v138, v139
	v_cvt_pk_bf16_f32 v115, v140, v141
	v_cvt_pk_bf16_f32 v116, v142, v143
	v_cvt_pk_bf16_f32 v117, v144, v145
	ds_read_b128 v[196:199], v170 offset:160
	ds_read_b128 v[216:219], v170 offset:8864
	ds_read_b128 v[200:203], v170 offset:17568
	ds_read_b128 v[204:207], v170 offset:26272
	s_waitcnt lgkmcnt(13)
	v_mfma_f32_32x32x16_bf16 v[154:169], v[106:109], v[2:5], v[154:169]
	v_exp_f32_e32 v146, v146
	s_waitcnt lgkmcnt(12)
	v_mfma_f32_32x32x16_bf16 v[154:169], v[110:113], v[6:9], v[154:169]
	v_exp_f32_e32 v147, v147
	v_exp_f32_e32 v148, v148
	s_waitcnt lgkmcnt(11)
	v_mfma_f32_32x32x16_bf16 v[18:33], v[128:131], v[114:117], v[18:33]
	v_exp_f32_e32 v149, v149
	v_exp_f32_e32 v150, v150
	global_load_dwordx4 v[82:85], v125, s[72:73]
	global_load_dwordx4 v[86:89], v125, s[74:75]
	global_load_dwordx4 v[90:93], v125, s[76:77]
	global_load_dwordx4 v[94:97], v125, s[78:79]
	v_add_u32_e32 v125, s38, v125
	v_exp_f32_e32 v151, v151
	s_waitcnt lgkmcnt(10)
	v_mfma_f32_32x32x16_bf16 v[34:49], v[184:187], v[114:117], v[34:49]
	v_exp_f32_e32 v152, v152
	v_exp_f32_e32 v153, v153
	v_add_f32_e32 v122, v146, v122
	s_waitcnt lgkmcnt(9)
	v_mfma_f32_32x32x16_bf16 v[50:65], v[188:191], v[114:117], v[50:65]
	v_add_f32_e32 v123, v147, v123
	v_add_f32_e32 v122, v148, v122
	v_add_f32_e32 v123, v149, v123
	s_waitcnt lgkmcnt(8)
	v_mfma_f32_32x32x16_bf16 v[66:81], v[192:195], v[114:117], v[66:81]
	v_add_f32_e32 v122, v150, v122
	v_add_f32_e32 v123, v151, v123
	v_add_f32_e32 v122, v152, v122
	v_add_f32_e32 v123, v153, v123
	v_cvt_pk_bf16_f32 v118, v146, v147
	v_cvt_pk_bf16_f32 v119, v148, v149
	v_cvt_pk_bf16_f32 v120, v150, v151
	v_cvt_pk_bf16_f32 v121, v152, v153
	ds_read_b128 v[128:131], v170 offset:192
	ds_read_b128 v[184:187], v170 offset:8896
	ds_read_b128 v[188:191], v170 offset:17600
	ds_read_b128 v[192:195], v170 offset:26304
	s_waitcnt lgkmcnt(7)
	v_mfma_f32_32x32x16_bf16 v[18:33], v[196:199], v[118:121], v[18:33]
	v_exp_f32_e32 v154, v154
	v_exp_f32_e32 v155, v155
	v_exp_f32_e32 v156, v156
	s_waitcnt lgkmcnt(6)
	v_mfma_f32_32x32x16_bf16 v[34:49], v[216:219], v[118:121], v[34:49]
	v_exp_f32_e32 v157, v157
	v_exp_f32_e32 v158, v158
	v_exp_f32_e32 v159, v159
	s_waitcnt lgkmcnt(5)
	v_mfma_f32_32x32x16_bf16 v[50:65], v[200:203], v[118:121], v[50:65]
	v_exp_f32_e32 v160, v160
	v_exp_f32_e32 v161, v161
	v_add_f32_e32 v122, v154, v122
	v_add_f32_e32 v123, v155, v123
	s_waitcnt lgkmcnt(4)
	v_mfma_f32_32x32x16_bf16 v[66:81], v[204:207], v[118:121], v[66:81]
	v_add_f32_e32 v122, v156, v122
	v_add_f32_e32 v123, v157, v123
	v_add_f32_e32 v122, v158, v122
	v_add_f32_e32 v123, v159, v123
	v_add_f32_e32 v122, v160, v122
	v_add_f32_e32 v123, v161, v123
	v_cvt_pk_bf16_f32 v114, v154, v155
	v_cvt_pk_bf16_f32 v115, v156, v157
	v_cvt_pk_bf16_f32 v116, v158, v159
	v_cvt_pk_bf16_f32 v117, v160, v161
	ds_read_b128 v[196:199], v170 offset:224
	ds_read_b128 v[216:219], v170 offset:8928
	ds_read_b128 v[200:203], v170 offset:17632
	ds_read_b128 v[204:207], v170 offset:26336
	s_waitcnt lgkmcnt(7)
	v_mfma_f32_32x32x16_bf16 v[18:33], v[128:131], v[114:117], v[18:33]
	v_exp_f32_e32 v162, v162
	v_exp_f32_e32 v163, v163
	v_exp_f32_e32 v164, v164
	s_waitcnt lgkmcnt(6)
	v_mfma_f32_32x32x16_bf16 v[34:49], v[184:187], v[114:117], v[34:49]
	v_exp_f32_e32 v165, v165
	v_exp_f32_e32 v166, v166
	v_exp_f32_e32 v167, v167
	s_waitcnt lgkmcnt(5)
	v_mfma_f32_32x32x16_bf16 v[50:65], v[188:191], v[114:117], v[50:65]
	v_exp_f32_e32 v168, v168
	v_exp_f32_e32 v169, v169
	v_add_f32_e32 v122, v162, v122
	v_add_f32_e32 v123, v163, v123
	s_waitcnt lgkmcnt(4)
	v_mfma_f32_32x32x16_bf16 v[66:81], v[192:195], v[114:117], v[66:81]
	v_add_f32_e32 v122, v164, v122
	v_add_f32_e32 v123, v165, v123
	v_add_f32_e32 v122, v166, v122
	v_add_f32_e32 v123, v167, v123
	v_add_f32_e32 v122, v168, v122
	v_add_f32_e32 v123, v169, v123
	v_cvt_pk_bf16_f32 v118, v162, v163
	v_cvt_pk_bf16_f32 v119, v164, v165
	v_cvt_pk_bf16_f32 v120, v166, v167
	v_cvt_pk_bf16_f32 v121, v168, v169
	s_waitcnt lgkmcnt(3)
	s_nop 0
	v_mfma_f32_32x32x16_bf16 v[18:33], v[196:199], v[118:121], v[18:33]
	s_waitcnt lgkmcnt(2)
	v_mfma_f32_32x32x16_bf16 v[34:49], v[216:219], v[118:121], v[34:49]
	s_waitcnt vmcnt(3)
	ds_write_b128 v173, v[82:85] offset:0
	s_waitcnt vmcnt(2)
	ds_write_b128 v173, v[86:89] offset:8704
	s_waitcnt vmcnt(1)
	ds_write_b128 v173, v[90:93] offset:17408
	s_waitcnt vmcnt(0)
	ds_write_b128 v173, v[94:97] offset:26112
	s_waitcnt lgkmcnt(5)
	v_mfma_f32_32x32x16_bf16 v[50:65], v[200:203], v[118:121], v[50:65]
	s_waitcnt lgkmcnt(4)
	v_mfma_f32_32x32x16_bf16 v[66:81], v[204:207], v[118:121], v[66:81]
	s_waitcnt lgkmcnt(0)
	s_barrier
	s_add_i32 s15, s15, 1
	s_cmp_eq_u32 s15, 34
	s_cbranch_scc0 .Lattn_nf_loop
	v_readlane_b32 s64, v175, 0
	v_readlane_b32 s65, v175, 1
	v_readlane_b32 s66, v175, 2
	v_readlane_b32 s67, v175, 3
	v_readlane_b32 s68, v175, 4
	v_readlane_b32 s69, v175, 5
	v_readlane_b32 s70, v175, 6
	v_readlane_b32 s71, v175, 7
	v_readlane_b32 s72, v175, 8
	v_readlane_b32 s73, v175, 9
	v_readlane_b32 s74, v175, 10
	v_readlane_b32 s75, v175, 11
	v_readlane_b32 s76, v175, 12
	v_readlane_b32 s77, v175, 13
	v_readlane_b32 s78, v175, 14
	v_readlane_b32 s79, v175, 15
	s_nop 4
	v_add_f32_e32 v186, v132, v134
	v_add_f32_e32 v184, v133, v135
	ds_bpermute_b32 v187, v172, v186
	ds_bpermute_b32 v185, v172, v184
	s_mov_b32 s10, 0x3fb8aa3b
	s_mov_b32 s11, 0xc2ce8ed0
	s_mov_b32 s6, 0x42b17218
	v_cmp_eq_u32_e64 s[40:41], 0, v179
	s_lshl_b32 s30, s14, 1
	v_lshlrev_b32_e32 v196, 3, v178
	v_mov_b32_e32 v197, 0
	v_lshlrev_b32_e32 v198, 4, v179
	v_or3_b32 v198, v198, v177, v180
	v_ashrrev_i32_e32 v199, 31, v198
	v_lshlrev_b64 v[198:199], 11, v[198:199]
	s_mov_b64 s[100:101], 0x18a10000
	v_lshl_add_u64 v[198:199], s[42:43], 0, v[198:199]
	v_lshl_add_u64 v[198:199], v[198:199], 0, s[30:31]
	v_lshl_add_u64 v[198:199], v[198:199], 0, v[196:197]
	v_lshl_add_u64 v[198:199], v[198:199], 0, s[100:101]
	global_load_dwordx2 v[146:147], v[198:199], off
	global_load_dwordx2 v[148:149], v[198:199], off offset:32
	global_load_dwordx2 v[150:151], v[198:199], off offset:64
	global_load_dwordx2 v[152:153], v[198:199], off offset:96
	global_load_dwordx2 v[188:189], v[198:199], off offset:128
	global_load_dwordx2 v[190:191], v[198:199], off offset:160
	global_load_dwordx2 v[192:193], v[198:199], off offset:192
	global_load_dwordx2 v[194:195], v[198:199], off offset:224
	s_mov_b64 s[100:101], exec
	s_and_b64 exec, exec, s[4:5]
	s_cbranch_execz .Lpop_skip
	v_readlane_b32 s14, v255, 22
	v_readlane_b32 s15, v255, 23
	v_mov_b32_e32 v224, 1
	s_nop 4
	global_atomic_add v224, v0, v224, s[14:15] sc0
.Lpop_skip:
	s_mov_b64 exec, s[100:101]
	v_mov_b32_e32 v235, 1
	s_load_dwordx2 s[100:101], s[44:45], 0x80
	v_readlane_b32 s14, v255, 36
	v_readlane_b32 s15, v255, 37
	s_nop 3
	s_lshl_b64 s[14:15], s[14:15], 2
	s_waitcnt lgkmcnt(0)
	v_add_f32_e32 v122, v123, v122
	v_xor_b32_e32 v82, 32, v223
	v_lshlrev_b32_e32 v82, 2, v82
	ds_bpermute_b32 v83, v82, v122
	v_add_f32_e32 v84, v186, v187
	v_mul_f32_e32 v85, 0x3fb8aa3b, v84
	v_fma_f32 v86, v84, s10, -v85
	v_rndne_f32_e32 v87, v85
	v_fmac_f32_e32 v86, 0x32a5705f, v84
	v_sub_f32_e32 v85, v85, v87
	v_add_f32_e32 v85, v85, v86
	v_exp_f32_e32 v85, v85
	v_cvt_i32_f32_e32 v86, v87
	v_cmp_ngt_f32_e32 vcc, s11, v84
	s_nop 0
	v_ldexp_f32 v85, v85, v86
	s_nop 1
	v_cndmask_b32_e32 v85, 0, v85, vcc
	v_cmp_nlt_f32_e32 vcc, s6, v84
	s_nop 1
	v_cndmask_b32_e32 v88, v220, v85, vcc
	v_add_f32_e32 v84, v184, v185
	v_mul_f32_e32 v85, 0x3fb8aa3b, v84
	v_fma_f32 v86, v84, s10, -v85
	v_rndne_f32_e32 v87, v85
	v_fmac_f32_e32 v86, 0x32a5705f, v84
	v_sub_f32_e32 v85, v85, v87
	v_add_f32_e32 v85, v85, v86
	v_exp_f32_e32 v85, v85
	v_cvt_i32_f32_e32 v86, v87
	v_cmp_ngt_f32_e32 vcc, s11, v84
	s_nop 0
	v_ldexp_f32 v85, v85, v86
	s_nop 1
	v_cndmask_b32_e32 v85, 0, v85, vcc
	v_cmp_nlt_f32_e32 vcc, s6, v84
	s_nop 1
	v_cndmask_b32_e32 v89, v220, v85, vcc
	v_sub_f32_e32 v88, v88, v89
	v_add_f32_e32 v88, v236, v88
	s_nop 1
	v_cndmask_b32_e64 v88, -v88, 1.0, s[40:41]
	s_waitcnt lgkmcnt(0)
	v_add_f32_e32 v83, v122, v83
	v_div_scale_f32 v90, s[10:11], v83, v83, v88
	v_rcp_f32_e32 v91, v90
	s_nop 0
	v_fma_f32 v92, -v90, v91, 1.0
	v_fmac_f32_e32 v91, v92, v91
	v_div_scale_f32 v92, vcc, v88, v83, v88
	v_mul_f32_e32 v93, v92, v91
	v_fma_f32 v94, -v90, v93, v92
	v_fmac_f32_e32 v93, v94, v91
	v_fma_f32 v90, -v90, v93, v92
	s_nop 1
	v_div_fmas_f32 v90, v90, v91, v93
	v_div_fixup_f32 v96, v90, v83, v88
	v_and_b32_e32 v98, 31, v223
	v_mul_u32_u24_e32 v98, 528, v98
	v_lshrrev_b32_e32 v99, 5, v223
	v_lshl_add_u32 v98, v99, 4, v98
	s_movk_i32 s6, 0x4200
	v_mad_u32_u24 v98, v182, s6, v98
	v_pk_mul_f32 v[18:19], v[18:19], v[96:97] op_sel_hi:[1,0]
	v_pk_mul_f32 v[20:21], v[20:21], v[96:97] op_sel_hi:[1,0]
	v_pk_mul_f32 v[22:23], v[22:23], v[96:97] op_sel_hi:[1,0]
	v_pk_mul_f32 v[24:25], v[24:25], v[96:97] op_sel_hi:[1,0]
	v_pk_mul_f32 v[26:27], v[26:27], v[96:97] op_sel_hi:[1,0]
	v_pk_mul_f32 v[28:29], v[28:29], v[96:97] op_sel_hi:[1,0]
	v_pk_mul_f32 v[30:31], v[30:31], v[96:97] op_sel_hi:[1,0]
	v_pk_mul_f32 v[32:33], v[32:33], v[96:97] op_sel_hi:[1,0]
	ds_write_b128 v98, v[18:21] offset:0
	ds_write_b128 v98, v[22:25] offset:32
	ds_write_b128 v98, v[26:29] offset:64
	ds_write_b128 v98, v[30:33] offset:96
	v_pk_mul_f32 v[34:35], v[34:35], v[96:97] op_sel_hi:[1,0]
	v_pk_mul_f32 v[36:37], v[36:37], v[96:97] op_sel_hi:[1,0]
	v_pk_mul_f32 v[38:39], v[38:39], v[96:97] op_sel_hi:[1,0]
	v_pk_mul_f32 v[40:41], v[40:41], v[96:97] op_sel_hi:[1,0]
	v_pk_mul_f32 v[42:43], v[42:43], v[96:97] op_sel_hi:[1,0]
	v_pk_mul_f32 v[44:45], v[44:45], v[96:97] op_sel_hi:[1,0]
	v_pk_mul_f32 v[46:47], v[46:47], v[96:97] op_sel_hi:[1,0]
	v_pk_mul_f32 v[48:49], v[48:49], v[96:97] op_sel_hi:[1,0]
	ds_write_b128 v98, v[34:37] offset:128
	ds_write_b128 v98, v[38:41] offset:160
	ds_write_b128 v98, v[42:45] offset:192
	ds_write_b128 v98, v[46:49] offset:224
	s_waitcnt lgkmcnt(0)
	v_pk_mul_f32 v[50:51], v[50:51], v[96:97] op_sel_hi:[1,0]
	v_pk_mul_f32 v[52:53], v[52:53], v[96:97] op_sel_hi:[1,0]
	v_pk_mul_f32 v[54:55], v[54:55], v[96:97] op_sel_hi:[1,0]
	v_pk_mul_f32 v[56:57], v[56:57], v[96:97] op_sel_hi:[1,0]
	v_pk_mul_f32 v[58:59], v[58:59], v[96:97] op_sel_hi:[1,0]
	v_pk_mul_f32 v[60:61], v[60:61], v[96:97] op_sel_hi:[1,0]
	v_pk_mul_f32 v[62:63], v[62:63], v[96:97] op_sel_hi:[1,0]
	v_pk_mul_f32 v[64:65], v[64:65], v[96:97] op_sel_hi:[1,0]
	ds_write_b128 v98, v[50:53] offset:256
	ds_write_b128 v98, v[54:57] offset:288
	ds_write_b128 v98, v[58:61] offset:320
	ds_write_b128 v98, v[62:65] offset:352
	v_pk_mul_f32 v[66:67], v[66:67], v[96:97] op_sel_hi:[1,0]
	v_pk_mul_f32 v[68:69], v[68:69], v[96:97] op_sel_hi:[1,0]
	v_pk_mul_f32 v[70:71], v[70:71], v[96:97] op_sel_hi:[1,0]
	v_pk_mul_f32 v[72:73], v[72:73], v[96:97] op_sel_hi:[1,0]
	v_pk_mul_f32 v[74:75], v[74:75], v[96:97] op_sel_hi:[1,0]
	v_pk_mul_f32 v[76:77], v[76:77], v[96:97] op_sel_hi:[1,0]
	v_pk_mul_f32 v[78:79], v[78:79], v[96:97] op_sel_hi:[1,0]
	v_pk_mul_f32 v[80:81], v[80:81], v[96:97] op_sel_hi:[1,0]
	ds_write_b128 v98, v[66:69] offset:384
	ds_write_b128 v98, v[70:73] offset:416
	ds_write_b128 v98, v[74:77] offset:448
	ds_write_b128 v98, v[78:81] offset:480
	s_waitcnt lgkmcnt(0)
	s_barrier
	s_add_u32 s100, s100, s14
	s_addc_u32 s101, s101, s15
	v_lshlrev_b32_e32 v132, 4, v178
	global_load_dwordx4 v[100:103], v132, s[100:101]
	global_load_dwordx4 v[104:107], v132, s[100:101] offset:64
	global_load_dwordx4 v[108:111], v132, s[100:101] offset:128
	global_load_dwordx4 v[112:115], v132, s[100:101] offset:192
	global_load_dwordx4 v[116:119], v132, s[100:101] offset:256
	global_load_dwordx4 v[120:123], v132, s[100:101] offset:320
	global_load_dwordx4 v[124:127], v132, s[100:101] offset:384
	global_load_dwordx4 v[128:131], v132, s[100:101] offset:448
	v_lshl_add_u32 v99, v179, 4, v177
	v_mul_u32_u24_e32 v99, 528, v99
	v_lshl_add_u32 v99, v178, 4, v99
	v_mad_u32_u24 v154, v182, s6, v99
	v_xor_b32_e32 v155, 1, v182
	v_mad_u32_u24 v155, v155, s6, v99
	ds_read_b128 v[82:85], v154 offset:0
	ds_read_b128 v[156:159], v155 offset:0
	ds_read_b128 v[86:89], v154 offset:64
	ds_read_b128 v[160:163], v155 offset:64
	ds_read_b128 v[90:93], v154 offset:128
	ds_read_b128 v[164:167], v155 offset:128
	ds_read_b128 v[94:97], v154 offset:192
	ds_read_b128 v[168:171], v155 offset:192
	s_waitcnt lgkmcnt(6)
	v_add_f32_e32 v38, v82, v156
	v_add_f32_e32 v39, v83, v157
	v_add_f32_e32 v36, v84, v158
	v_add_f32_e32 v37, v85, v159
	v_mul_f32_e32 v2, v38, v38
	v_fmac_f32_e32 v2, v39, v39
	v_fmac_f32_e32 v2, v36, v36
	v_fmac_f32_e32 v2, v37, v37
	s_waitcnt lgkmcnt(4)
	v_add_f32_e32 v34, v86, v160
	v_add_f32_e32 v35, v87, v161
	v_add_f32_e32 v32, v88, v162
	v_add_f32_e32 v33, v89, v163
	v_fmac_f32_e32 v2, v34, v34
	v_fmac_f32_e32 v2, v35, v35
	v_fmac_f32_e32 v2, v32, v32
	v_fmac_f32_e32 v2, v33, v33
	s_waitcnt lgkmcnt(2)
	v_add_f32_e32 v30, v90, v164
	v_add_f32_e32 v31, v91, v165
	v_add_f32_e32 v28, v92, v166
	v_add_f32_e32 v29, v93, v167
	v_fmac_f32_e32 v2, v30, v30
	v_fmac_f32_e32 v2, v31, v31
	v_fmac_f32_e32 v2, v28, v28
	v_fmac_f32_e32 v2, v29, v29
	s_waitcnt lgkmcnt(0)
	v_add_f32_e32 v26, v94, v168
	v_add_f32_e32 v27, v95, v169
	v_add_f32_e32 v24, v96, v170
	v_add_f32_e32 v25, v97, v171
	v_fmac_f32_e32 v2, v26, v26
	v_fmac_f32_e32 v2, v27, v27
	v_fmac_f32_e32 v2, v24, v24
	v_fmac_f32_e32 v2, v25, v25
	ds_read_b128 v[82:85], v154 offset:256
	ds_read_b128 v[156:159], v155 offset:256
	ds_read_b128 v[86:89], v154 offset:320
	ds_read_b128 v[160:163], v155 offset:320
	ds_read_b128 v[90:93], v154 offset:384
	ds_read_b128 v[164:167], v155 offset:384
	ds_read_b128 v[94:97], v154 offset:448
	ds_read_b128 v[168:171], v155 offset:448
	s_waitcnt lgkmcnt(6)
	v_add_f32_e32 v22, v82, v156
	v_add_f32_e32 v23, v83, v157
	v_add_f32_e32 v20, v84, v158
	v_add_f32_e32 v21, v85, v159
	v_fmac_f32_e32 v2, v22, v22
	v_fmac_f32_e32 v2, v23, v23
	v_fmac_f32_e32 v2, v20, v20
	v_fmac_f32_e32 v2, v21, v21
	s_waitcnt lgkmcnt(4)
	v_add_f32_e32 v18, v86, v160
	v_add_f32_e32 v19, v87, v161
	v_add_f32_e32 v16, v88, v162
	v_add_f32_e32 v17, v89, v163
	v_fmac_f32_e32 v2, v18, v18
	v_fmac_f32_e32 v2, v19, v19
	v_fmac_f32_e32 v2, v16, v16
	v_fmac_f32_e32 v2, v17, v17
	s_waitcnt lgkmcnt(2)
	v_add_f32_e32 v14, v90, v164
	v_add_f32_e32 v15, v91, v165
	v_add_f32_e32 v12, v92, v166
	v_add_f32_e32 v13, v93, v167
	v_fmac_f32_e32 v2, v14, v14
	v_fmac_f32_e32 v2, v15, v15
	v_fmac_f32_e32 v2, v12, v12
	v_fmac_f32_e32 v2, v13, v13
	s_waitcnt lgkmcnt(0)
	v_add_f32_e32 v8, v94, v168
	v_add_f32_e32 v9, v95, v169
	v_add_f32_e32 v6, v96, v170
	v_add_f32_e32 v7, v97, v171
	v_fmac_f32_e32 v2, v8, v8
	v_fmac_f32_e32 v2, v9, v9
	v_fmac_f32_e32 v2, v6, v6
	v_fmac_f32_e32 v2, v7, v7
	ds_bpermute_b32 v3, v176, v2
	s_load_dwordx2 s[10:11], s[44:45], 0x80
	v_lshlrev_b32_e32 v4, 3, v178
	v_mov_b32_e32 v5, v0
	s_mov_b32 s6, 0x18a10000
	s_waitcnt lgkmcnt(0)
	v_add_f32_e32 v2, v2, v3
	ds_bpermute_b32 v1, v1, v2
	s_add_u32 s10, s10, s14
	s_addc_u32 s11, s11, s15
	s_mov_b64 s[14:15], 0x18a10000
	v_lshlrev_b32_e32 v44, 4, v178
	s_waitcnt lgkmcnt(0)
	v_add_f32_e32 v1, v2, v1
	v_fmamk_f32 v1, v1, 0x3c000000, v234
	v_cmp_gt_f32_e32 vcc, s90, v1
	v_mul_f32_e32 v2, 0x4b800000, v1
	s_nop 0
	v_cndmask_b32_e32 v1, v1, v2, vcc
	v_rsq_f32_e32 v1, v1
	s_nop 0
	v_mul_f32_e32 v2, 0x45800000, v1
	v_cndmask_b32_e32 v1, v1, v2, vcc
	v_lshlrev_b32_e32 v2, 4, v179
	v_or3_b32 v2, v2, v177, v180
	v_ashrrev_i32_e32 v3, 31, v2
	v_lshlrev_b64 v[2:3], 11, v[2:3]
	v_lshl_add_u64 v[2:3], s[42:43], 0, v[2:3]
	v_lshl_add_u64 v[2:3], v[2:3], 0, s[30:31]
	v_lshl_add_u64 v[2:3], v[2:3], 0, v[4:5]
	v_add_co_u32_e32 v40, vcc, s6, v2
	v_lshl_add_u64 v[10:11], v[2:3], 0, s[14:15]
	s_nop 0
	v_addc_co_u32_e32 v41, vcc, 0, v3, vcc
	v_mul_f32_e32 v1, v227, v1
	v_mul_f32_e32 v38, v38, v1
	v_mul_f32_e32 v36, v36, v1
	v_mul_f32_e32 v34, v34, v1
	v_mul_f32_e32 v32, v32, v1
	v_mul_f32_e32 v30, v30, v1
	v_mul_f32_e32 v28, v28, v1
	v_mul_f32_e32 v26, v26, v1
	v_mul_f32_e32 v24, v24, v1
	v_mul_f32_e32 v22, v22, v1
	v_mul_f32_e32 v20, v20, v1
	v_mul_f32_e32 v18, v18, v1
	v_mul_f32_e32 v16, v16, v1
	v_mul_f32_e32 v14, v14, v1
	v_mul_f32_e32 v12, v12, v1
	s_waitcnt vmcnt(0)
	v_readfirstlane_b32 s101, v224
	v_mov_b32_e32 v42, v146
	v_mov_b32_e32 v43, v147
	v_mov_b32_e32 v2, v100
	v_mov_b32_e32 v3, v101
	v_mov_b32_e32 v4, v102
	v_mov_b32_e32 v5, v103
	v_mul_f32_e32 v2, v2, v38
	v_lshlrev_b32_e32 v38, 16, v42
	v_mul_f32_e32 v2, v2, v38
	v_mul_f32_e32 v38, v39, v1
	v_mul_f32_e32 v4, v4, v36
	v_lshlrev_b32_e32 v36, 16, v43
	v_mul_f32_e32 v3, v3, v38
	v_and_b32_e32 v38, 0xffff0000, v42
	v_mul_f32_e32 v4, v4, v36
	v_mul_f32_e32 v36, v37, v1
	v_mul_f32_e32 v3, v3, v38
	v_mul_f32_e32 v5, v5, v36
	v_and_b32_e32 v36, 0xffff0000, v43
	v_mul_f32_e32 v5, v5, v36
	s_nop 1
	v_cvt_pk_bf16_f32 v2, v2, v3
	s_nop 1
	v_cvt_pk_bf16_f32 v3, v4, v5
	global_store_dwordx2 v[40:41], v[2:3], off
	v_mov_b32_e32 v36, v148
	v_mov_b32_e32 v37, v149
	s_nop 0
	v_mov_b32_e32 v2, v104
	v_mov_b32_e32 v3, v105
	v_mov_b32_e32 v4, v106
	v_mov_b32_e32 v5, v107
	v_mul_f32_e32 v2, v2, v34
	v_lshlrev_b32_e32 v34, 16, v36
	v_mul_f32_e32 v2, v2, v34
	v_mul_f32_e32 v34, v35, v1
	v_mul_f32_e32 v4, v4, v32
	v_lshlrev_b32_e32 v32, 16, v37
	v_mul_f32_e32 v3, v3, v34
	v_and_b32_e32 v34, 0xffff0000, v36
	v_mul_f32_e32 v4, v4, v32
	v_mul_f32_e32 v32, v33, v1
	v_mul_f32_e32 v3, v3, v34
	v_mul_f32_e32 v5, v5, v32
	v_and_b32_e32 v32, 0xffff0000, v37
	v_mul_f32_e32 v5, v5, v32
	s_nop 1
	v_cvt_pk_bf16_f32 v2, v2, v3
	s_nop 1
	v_cvt_pk_bf16_f32 v3, v4, v5
	global_store_dwordx2 v[10:11], v[2:3], off offset:32
	v_mov_b32_e32 v32, v150
	v_mov_b32_e32 v33, v151
	s_nop 0
	v_mov_b32_e32 v2, v108
	v_mov_b32_e32 v3, v109
	v_mov_b32_e32 v4, v110
	v_mov_b32_e32 v5, v111
	v_mul_f32_e32 v2, v2, v30
	v_lshlrev_b32_e32 v30, 16, v32
	v_mul_f32_e32 v2, v2, v30
	v_mul_f32_e32 v30, v31, v1
	v_mul_f32_e32 v4, v4, v28
	v_lshlrev_b32_e32 v28, 16, v33
	v_mul_f32_e32 v3, v3, v30
	v_and_b32_e32 v30, 0xffff0000, v32
	v_mul_f32_e32 v4, v4, v28
	v_mul_f32_e32 v28, v29, v1
	v_mul_f32_e32 v3, v3, v30
	v_mul_f32_e32 v5, v5, v28
	v_and_b32_e32 v28, 0xffff0000, v33
	v_mul_f32_e32 v5, v5, v28
	s_nop 1
	v_cvt_pk_bf16_f32 v2, v2, v3
	s_nop 1
	v_cvt_pk_bf16_f32 v3, v4, v5
	global_store_dwordx2 v[10:11], v[2:3], off offset:64
	v_mov_b32_e32 v28, v152
	v_mov_b32_e32 v29, v153
	s_nop 0
	v_mov_b32_e32 v2, v112
	v_mov_b32_e32 v3, v113
	v_mov_b32_e32 v4, v114
	v_mov_b32_e32 v5, v115
	v_mul_f32_e32 v2, v2, v26
	v_lshlrev_b32_e32 v26, 16, v28
	v_mul_f32_e32 v2, v2, v26
	v_mul_f32_e32 v26, v27, v1
	v_mul_f32_e32 v4, v4, v24
	v_lshlrev_b32_e32 v24, 16, v29
	v_mul_f32_e32 v3, v3, v26
	v_and_b32_e32 v26, 0xffff0000, v28
	v_mul_f32_e32 v4, v4, v24
	v_mul_f32_e32 v24, v25, v1
	v_mul_f32_e32 v3, v3, v26
	v_mul_f32_e32 v5, v5, v24
	v_and_b32_e32 v24, 0xffff0000, v29
	v_mul_f32_e32 v5, v5, v24
	s_nop 1
	v_cvt_pk_bf16_f32 v2, v2, v3
	s_nop 1
	v_cvt_pk_bf16_f32 v3, v4, v5
	global_store_dwordx2 v[10:11], v[2:3], off offset:96
	v_mov_b32_e32 v24, v188
	v_mov_b32_e32 v25, v189
	s_nop 0
	v_mov_b32_e32 v2, v116
	v_mov_b32_e32 v3, v117
	v_mov_b32_e32 v4, v118
	v_mov_b32_e32 v5, v119
	v_mul_f32_e32 v2, v2, v22
	v_lshlrev_b32_e32 v22, 16, v24
	v_mul_f32_e32 v2, v2, v22
	v_mul_f32_e32 v22, v23, v1
	v_mul_f32_e32 v4, v4, v20
	v_lshlrev_b32_e32 v20, 16, v25
	v_mul_f32_e32 v3, v3, v22
	v_and_b32_e32 v22, 0xffff0000, v24
	v_mul_f32_e32 v4, v4, v20
	v_mul_f32_e32 v20, v21, v1
	v_mul_f32_e32 v3, v3, v22
	v_mul_f32_e32 v5, v5, v20
	v_and_b32_e32 v20, 0xffff0000, v25
	v_mul_f32_e32 v5, v5, v20
	s_nop 1
	v_cvt_pk_bf16_f32 v2, v2, v3
	s_nop 1
	v_cvt_pk_bf16_f32 v3, v4, v5
	global_store_dwordx2 v[10:11], v[2:3], off offset:128
	v_mov_b32_e32 v20, v190
	v_mov_b32_e32 v21, v191
	s_nop 0
	v_mov_b32_e32 v2, v120
	v_mov_b32_e32 v3, v121
	v_mov_b32_e32 v4, v122
	v_mov_b32_e32 v5, v123
	v_mul_f32_e32 v2, v2, v18
	v_lshlrev_b32_e32 v18, 16, v20
	v_mul_f32_e32 v2, v2, v18
	v_mul_f32_e32 v18, v19, v1
	v_mul_f32_e32 v4, v4, v16
	v_lshlrev_b32_e32 v16, 16, v21
	v_mul_f32_e32 v3, v3, v18
	v_and_b32_e32 v18, 0xffff0000, v20
	v_mul_f32_e32 v4, v4, v16
	v_mul_f32_e32 v16, v17, v1
	v_mul_f32_e32 v3, v3, v18
	v_mul_f32_e32 v5, v5, v16
	v_and_b32_e32 v16, 0xffff0000, v21
	v_mul_f32_e32 v5, v5, v16
	s_nop 1
	v_cvt_pk_bf16_f32 v2, v2, v3
	s_nop 1
	v_cvt_pk_bf16_f32 v3, v4, v5
	global_store_dwordx2 v[10:11], v[2:3], off offset:160
	v_mov_b32_e32 v16, v192
	v_mov_b32_e32 v17, v193
	s_nop 0
	v_mov_b32_e32 v2, v124
	v_mov_b32_e32 v3, v125
	v_mov_b32_e32 v4, v126
	v_mov_b32_e32 v5, v127
	v_mul_f32_e32 v2, v2, v14
	v_lshlrev_b32_e32 v14, 16, v16
	v_mul_f32_e32 v2, v2, v14
	v_mul_f32_e32 v14, v15, v1
	v_mul_f32_e32 v4, v4, v12
	v_lshlrev_b32_e32 v12, 16, v17
	v_mul_f32_e32 v3, v3, v14
	v_and_b32_e32 v14, 0xffff0000, v16
	v_mul_f32_e32 v4, v4, v12
	v_mul_f32_e32 v12, v13, v1
	v_mul_f32_e32 v3, v3, v14
	v_mul_f32_e32 v5, v5, v12
	v_and_b32_e32 v12, 0xffff0000, v17
	v_mul_f32_e32 v5, v5, v12
	s_nop 1
	v_cvt_pk_bf16_f32 v2, v2, v3
	s_nop 1
	v_cvt_pk_bf16_f32 v3, v4, v5
	global_store_dwordx2 v[10:11], v[2:3], off offset:192
	v_mov_b32_e32 v2, v194
	v_mov_b32_e32 v3, v195
	s_nop 0
	v_mov_b32_e32 v12, v128
	v_mov_b32_e32 v13, v129
	v_mov_b32_e32 v14, v130
	v_mov_b32_e32 v15, v131
	v_mul_f32_e32 v4, v8, v1
	v_lshlrev_b32_e32 v5, 16, v2
	v_mul_f32_e32 v4, v4, v12
	v_mul_f32_e32 v4, v4, v5
	v_mul_f32_e32 v5, v9, v1
	v_mul_f32_e32 v5, v5, v13
	v_and_b32_e32 v2, 0xffff0000, v2
	v_mul_f32_e32 v2, v5, v2
	v_mul_f32_e32 v5, v6, v1
	v_mul_f32_e32 v1, v7, v1
	v_mul_f32_e32 v5, v5, v14
	v_lshlrev_b32_e32 v6, 16, v3
	v_mul_f32_e32 v1, v1, v15
	v_and_b32_e32 v3, 0xffff0000, v3
	v_mul_f32_e32 v5, v5, v6
	v_mul_f32_e32 v1, v1, v3
	s_nop 1
	v_cvt_pk_bf16_f32 v2, v4, v2
	s_nop 1
	v_cvt_pk_bf16_f32 v3, v5, v1
	global_store_dwordx2 v[10:11], v[2:3], off offset:224
	s_barrier
